# strategy 2 (prologue de-serialisation): the GLA scan producers issue all eight gate-up-weight loads of their item prologue together and wait once, instead of four load-pair / vmcnt(0) round trips
# baseline (speedup 1.0000x reference)
; __device__ __forceinline__ unsigned pk2(float lo, float hi) { f32x2 v = {lo, hi}; bf16x2_t b = __builtin_convertvector(v, bf16x2_t); return __builtin_bit_cast(unsigned, b); }
; __device__ __forceinline__ float bflo(unsigned w) { return __uint_as_float(w << 16); }
; __device__ __forceinline__ float bfhi(unsigned w) { return __uint_as_float(w & 0xffff0000u); }
; __device__ __forceinline__ void gla_scan_phase2(LAS unsigned char* lds, const bf16_t* proj, const float* gbuf, const float* wgu  , const float* bg  ,
;                                                 bf16_t* ob0, bf16_t* ob1) {
;     ...
;             bf16x8 wbh, wbl;
;             {
;                 unsigned hi_[4], lo_[4];
; #pragma unroll
;                 for (int q = 0; q < 4; ++q) {
;                     const float w0 = wgu[(size_t)(dir * 16 + 8 * hh + 2 * q) * 512 + h * 128 + 32 * zd + r], w1 = wgu[(size_t)(dir * 16 + 8 * hh + 2 * q + 1) * 512 + h * 128 + 32 * zd + r];
;                     hi_[q] = pk2(w0, w1); lo_[q] = pk2(w0 - bflo(hi_[q]), w1 - bfhi(hi_[q]));
;                 }
;                 wbh = __builtin_bit_cast(bf16x8, (u32x4){hi_[0], hi_[1], hi_[2], hi_[3]}); wbl = __builtin_bit_cast(bf16x8, (u32x4){lo_[0], lo_[1], lo_[2], lo_[3]});
;             }
;             const float zbias = bg[dir * 512 + h * 128 + 32 * zd + r];
;             const __amdgpu_buffer_rsrc_t prs = __builtin_amdgcn_make_buffer_rsrc((void*)proj, 0, (unsigned)((size_t)MTOK * GINP * 2), 0x00020000);
;             const unsigned qvoff = (unsigned)((16 * seg * GINP + h * 128 + d) * 2), vvoff = (unsigned)((16 * seg * GINP + 1024 + h * 256 + 2 * d) * 2);
;             f32x4 gna, gnb;
;             { const float* grow = gbuf + (size_t)(b * SEQ + (dir ? NCH - 1 : 0) * CH + r) * 32 + dir * 16 + 8 * hh; gna = *(const f32x4*)grow; gnb = *(const f32x4*)(grow + 4); }
.LBB0_217:
	s_and_b64 vcc, exec, s[6:7]
	s_cbranch_vccz .LBB0_212
	s_nop 7
	v_lshl_or_b32 v0, s8, 13, v198
	s_lshl_b32 s0, s15, 7
	v_or_b32_e32 v0, s0, v0
	v_lshlrev_b32_e32 v160, 2, v0
	v_lshl_add_u64 v[0:1], s[16:17], 0, v[160:161]
	v_lshl_add_u64 v[0:1], s[22:23], 2, v[0:1]
	v_mov_b32_e32 v193, v161
	v_lshl_add_u64 v[0:1], v[0:1], 0, v[192:193]
	global_load_dword v2, v[0:1], off
	global_load_dword v3, v[0:1], off offset:2048
	s_movk_i32 s6, 0x2000
	v_add_co_u32_e32 v4, vcc, s6, v0
	s_nop 1
	v_addc_co_u32_e32 v5, vcc, 0, v1, vcc
	global_load_dword v6, v[4:5], off offset:-4096
	global_load_dword v7, v[4:5], off offset:-2048
	global_load_dword v8, v[4:5], off
	global_load_dword v9, v[4:5], off offset:2048
	s_movk_i32 s6, 0x3000
	v_add_co_u32_e32 v0, vcc, s6, v0
	s_nop 1
	v_addc_co_u32_e32 v1, vcc, 0, v1, vcc
	global_load_dword v10, v[0:1], off
	global_load_dword v11, v[0:1], off offset:2048
	s_lshl_b32 s9, s9, 11
	v_lshlrev_b32_e32 v160, 2, v188
	s_mov_b32 s20, 0
	v_or_b32_e32 v52, s9, v186
	s_lshl_b32 s6, s8, 9
	s_or_b32 s6, s0, s6
	s_cmp_lg_u32 s8, 0
	s_cselect_b64 s[68:69], -1, 0
	s_cmp_eq_u32 s8, 0
	s_cselect_b64 s[48:49], -1, 0
	s_waitcnt vmcnt(0)
	v_cvt_pk_bf16_f32 v32, v2, v3
	v_cvt_pk_bf16_f32 v33, v6, v7
	v_cvt_pk_bf16_f32 v34, v8, v9
	v_cvt_pk_bf16_f32 v35, v10, v11
	v_lshlrev_b32_e32 v4, 16, v32
	v_and_b32_e32 v5, 0xffff0000, v32
	v_pk_add_f32 v[2:3], v[2:3], v[4:5] neg_lo:[0,1] neg_hi:[0,1]
	s_nop 0
	v_cvt_pk_bf16_f32 v36, v2, v3
	v_lshlrev_b32_e32 v4, 16, v33
	v_and_b32_e32 v5, 0xffff0000, v33
	v_pk_add_f32 v[6:7], v[6:7], v[4:5] neg_lo:[0,1] neg_hi:[0,1]
	s_nop 0
	v_cvt_pk_bf16_f32 v37, v6, v7
	v_lshlrev_b32_e32 v4, 16, v34
	v_and_b32_e32 v5, 0xffff0000, v34
	v_pk_add_f32 v[8:9], v[8:9], v[4:5] neg_lo:[0,1] neg_hi:[0,1]
	s_nop 0
	v_cvt_pk_bf16_f32 v38, v8, v9
	v_lshlrev_b32_e32 v4, 16, v35
	v_and_b32_e32 v5, 0xffff0000, v35
	v_pk_add_f32 v[10:11], v[10:11], v[4:5] neg_lo:[0,1] neg_hi:[0,1]
	s_nop 0
	v_cvt_pk_bf16_f32 v39, v10, v11
	v_add_u32_e32 v0, s6, v199
	v_ashrrev_i32_e32 v1, 31, v0
	v_lshl_add_u64 v[0:1], v[0:1], 2, s[18:19]
	global_load_dword v0, v[0:1], off
	v_or_b32_e32 v1, s0, v200
	s_and_b64 s[6:7], s[48:49], exec
	v_lshlrev_b32_e32 v50, 1, v1
	v_lshl_or_b32 v1, s15, 9, v213
	s_cselect_b32 s0, 0, 0x7e0
	v_or_b32_e32 v51, 0x800, v1
	v_or_b32_e32 v1, s0, v186
	v_or_b32_e32 v2, s9, v1
	v_ashrrev_i32_e32 v3, 31, v2
	v_readlane_b32 s6, v253, 19
	v_lshlrev_b64 v[2:3], 7, v[2:3]
	v_readlane_b32 s7, v253, 20
	s_lshl_b32 s28, s8, 6
	v_lshl_add_u64 v[48:49], v[190:191], 0, s[28:29]
	v_lshl_add_u64 v[2:3], s[6:7], 0, v[2:3]
	v_lshl_add_u64 v[2:3], v[2:3], 0, s[28:29]
	v_lshl_add_u64 v[2:3], v[2:3], 0, v[160:161]
	global_load_dwordx4 v[40:43], v[2:3], off offset:16
	global_load_dwordx4 v[44:47], v[2:3], off
	v_or_b32_e32 v53, 0x400, v50
	s_xor_b64 s[50:51], s[40:41], s[48:49]
	s_xor_b64 s[52:53], s[42:43], s[48:49]
	s_xor_b64 s[54:55], s[44:45], s[48:49]
	s_xor_b64 s[56:57], s[46:47], s[48:49]
	s_mov_b32 s8, 63
	s_waitcnt vmcnt(2)
	v_mov_b32_e32 v1, v0
	v_mov_b32_e32 v2, v0
	v_mov_b32_e32 v3, v0
	v_mov_b32_e32 v4, v0
	v_mov_b32_e32 v5, v0
	v_mov_b32_e32 v6, v0
	v_mov_b32_e32 v7, v0
	v_mov_b32_e32 v8, v0
	v_mov_b32_e32 v9, v0
	v_mov_b32_e32 v10, v0
	v_mov_b32_e32 v11, v0
	v_mov_b32_e32 v12, v0
	v_mov_b32_e32 v13, v0
	v_mov_b32_e32 v14, v0
	v_mov_b32_e32 v15, v0
	v_and_b32_e32 v171, 7, v179
	v_lshrrev_b32_e32 v175, 3, v179
	v_mul_u32_u24_e32 v176, 0x6800, v171
	v_lshl_add_u32 v176, v175, 4, v176
	s_lshl_b32 s0, s15, 9
	s_addk_i32 s0, 0x800
	v_add_u32_e32 v176, s0, v176
	v_mul_u32_u24_e32 v177, 0x280, v175
	v_lshl_add_u32 v177, v171, 3, v177
	v_and_b32_e32 v172, 15, v179
	v_lshlrev_b32_e32 v172, 4, v172
	v_bfe_u32 v174, v179, 4, 2
	v_lshrrev_b32_e32 v173, 6, v179
	v_lshl_add_u32 v174, v173, 3, v174
	v_mul_u32_u24_e32 v174, 0x1a00, v174
	v_add_u32_e32 v172, v172, v174
	s_lshl_b32 s0, s15, 8
	v_add_u32_e32 v172, s0, v172
	v_lshlrev_b32_e32 v174, 11, v173
	v_add_u32_e32 v174, 0x1b600, v174
	v_and_b32_e32 v173, 0x7f, v179
	v_lshlrev_b32_e32 v173, 1, v173
	v_bfe_u32 v175, v179, 7, 1
	v_lshl_add_u32 v173, v175, 12, v173
	v_add_u32_e32 v173, 0x1b600, v173
	s_and_b64 s[6:7], s[48:49], exec
	s_cselect_b32 s0, s20, s8
	s_lshl_b32 s0, s0, 5
	s_add_i32 s0, s0, s9
	s_mulk_i32 s0, 0x1a00
	v_readfirstlane_b32 s26, v174
	s_add_u32 s78, s64, s0
	s_addc_u32 s79, s65, 0
	s_add_u32 s80, s78, 0x6800
	s_addc_u32 s81, s79, 0
	s_add_u32 s82, s78, 0x400
	s_addc_u32 s83, s79, 0
	s_add_u32 s24, s80, 0x400
	s_addc_u32 s25, s81, 0
	s_mov_b32 m0, s26
	s_nop 0
	global_load_lds_dwordx4 v172, s[78:79]
	s_add_i32 m0, s26, 0x400
	s_nop 0
	global_load_lds_dwordx4 v172, s[80:81]
	s_add_i32 m0, s26, 0x2000
	s_nop 0
	global_load_lds_dwordx4 v172, s[82:83]
	s_add_i32 m0, s26, 0x2400
	s_nop 0
	global_load_lds_dwordx4 v172, s[24:25]
	s_branch .LBB0_220
